# v132 + stick-breaking key loop: packed adds split and 51 of 70 per-iteration v_mov shuffles removed by copy propagation
# baseline (speedup 1.0000x reference)
.LBB0_589:
	s_add_i32 s72, s65, 0xc0
	s_cmp_gt_i32 s72, s68
	s_cselect_b64 s[72:73], -1, 0
	s_or_b64 s[72:73], s[42:43], s[72:73]
	s_and_b64 vcc, exec, s[72:73]
	s_cbranch_vccnz .LBB0_594
	s_mul_i32 s42, s71, 0x8c00
	v_add_u32_e32 v188, s42, v157
	ds_read_b128 v[66:69], v188
	ds_read_b128 v[160:163], v188 offset:32
	ds_read_b128 v[82:85], v188 offset:8704
	ds_read_b128 v[164:167], v188 offset:8736
	v_add_u32_e32 v199, s65, v159
	v_add_u32_e32 v189, 0xe0, v199
	s_waitcnt lgkmcnt(1)
	v_mfma_f32_32x32x16_bf16 v[82:97], v[82:85], v[98:101], 0
	v_add_u32_e32 v190, 0xe1, v199
	v_cmp_lt_i32_e32 vcc, v189, v150
	v_add_u32_e32 v191, 0xe2, v199
	v_add_u32_e32 v192, 0xe3, v199
	v_add_u32_e32 v193, 0xe8, v199
	v_add_u32_e32 v204, 0xe9, v199
	v_add_u32_e32 v205, 0xea, v199
	s_waitcnt lgkmcnt(0)
	v_mfma_f32_32x32x16_bf16 v[82:97], v[164:167], v[102:105], v[82:97]
	ds_read_b128 v[164:167], v188 offset:8768
	ds_read_b128 v[168:171], v188 offset:8800
	v_add_u32_e32 v206, 0xeb, v199
	s_waitcnt lgkmcnt(1)
	v_mfma_f32_32x32x16_bf16 v[82:97], v[164:167], v[106:109], v[82:97]
	s_waitcnt lgkmcnt(0)
	v_mfma_f32_32x32x16_bf16 v[82:97], v[168:171], v[110:113], v[82:97]
	ds_read_b128 v[164:167], v188 offset:8832
	ds_read_b128 v[168:171], v188 offset:8864
	s_waitcnt lgkmcnt(1)
	v_mfma_f32_32x32x16_bf16 v[82:97], v[164:167], v[114:117], v[82:97]
	ds_read_b128 v[164:167], v188 offset:8896
	s_waitcnt lgkmcnt(1)
	v_mfma_f32_32x32x16_bf16 v[82:97], v[168:171], v[118:121], v[82:97]
	ds_read_b128 v[168:171], v188 offset:64
	ds_read_b128 v[172:175], v188 offset:96
	ds_read_b128 v[176:179], v188 offset:8928
	s_waitcnt lgkmcnt(3)
	v_mfma_f32_32x32x16_bf16 v[82:97], v[164:167], v[122:125], v[82:97]
	ds_read_b128 v[164:167], v188 offset:128
	ds_read_b128 v[180:183], v188 offset:160
	ds_read_b128 v[184:187], v188 offset:192
	ds_read_b128 v[200:203], v188 offset:224
	v_mfma_f32_32x32x16_bf16 v[66:81], v[66:69], v[98:101], 0
	s_waitcnt lgkmcnt(4)
	v_mfma_f32_32x32x16_bf16 v[82:97], v[176:179], v[126:129], v[82:97]
	v_mfma_f32_32x32x16_bf16 v[66:81], v[160:163], v[102:105], v[66:81]
	s_nop 10
	v_cndmask_b32_e32 v82, v194, v82, vcc
	v_cmp_lt_i32_e32 vcc, v190, v150
	v_exp_f32_e64 v176, -|v82|
	s_nop 0
	v_cndmask_b32_e32 v83, v194, v83, vcc
	v_cmp_lt_i32_e32 vcc, v191, v150
	v_exp_f32_e64 v177, -|v83|
	v_mfma_f32_32x32x16_bf16 v[66:81], v[168:171], v[106:109], v[66:81]
	v_cndmask_b32_e32 v84, v194, v84, vcc
	v_cmp_lt_i32_e32 vcc, v192, v150
	v_exp_f32_e64 v178, -|v84|
	v_add_f32_e64 v160, v176, 1.0
	v_add_f32_e64 v161, v177, 1.0
	v_cndmask_b32_e32 v85, v194, v85, vcc
	v_cmp_lt_i32_e32 vcc, v193, v150
	v_exp_f32_e64 v179, -|v85|
	v_log_f32_e32 v160, v160
	v_cndmask_b32_e32 v86, v194, v86, vcc
	v_cmp_lt_i32_e32 vcc, v204, v150
	v_exp_f32_e64 v188, -|v86|
	v_add_f32_e64 v176, v178, 1.0
	v_add_f32_e64 v177, v179, 1.0
	v_cndmask_b32_e32 v87, v194, v87, vcc
	v_exp_f32_e64 v189, -|v87|
	v_cmp_lt_i32_e32 vcc, v205, v150
	v_log_f32_e32 v161, v161
	v_log_f32_e32 v176, v176
	v_cndmask_b32_e32 v88, v194, v88, vcc
	v_cmp_lt_i32_e32 vcc, v206, v150
	v_add_f32_e64 v178, v188, 1.0
	v_add_f32_e64 v179, v189, 1.0
	v_exp_f32_e64 v190, -|v88|
	v_cndmask_b32_e32 v89, v194, v89, vcc
	v_exp_f32_e64 v191, -|v89|
	v_log_f32_e32 v177, v177
	v_log_f32_e32 v178, v178
	v_log_f32_e32 v179, v179
	v_max_f32_e32 v192, 0, v82
	v_max_f32_e32 v193, 0, v83
	v_max_f32_e32 v204, 0, v84
	v_max_f32_e32 v205, 0, v85
	v_max_f32_e32 v162, 0, v86
	v_max_f32_e32 v163, 0, v87
	v_mfma_f32_32x32x16_bf16 v[66:81], v[172:175], v[110:113], v[66:81]
	v_add_f32_e64 v188, v192, v160
	v_add_f32_e64 v189, v193, v161
	v_add_f32_e64 v160, v204, v176
	v_add_f32_e64 v161, v205, v177
	v_add_f32_e64 v176, v162, v178
	v_add_f32_e64 v177, v163, v179
	v_add_f32_e64 v162, v190, 1.0
	v_add_f32_e64 v163, v191, 1.0
	v_log_f32_e32 v168, v162
	v_max_f32_e32 v170, 0, v88
	v_add_u32_e32 v162, 0xf0, v199
	v_cmp_lt_i32_e32 vcc, v162, v150
	v_log_f32_e32 v169, v163
	s_waitcnt lgkmcnt(3)
	v_mfma_f32_32x32x16_bf16 v[66:81], v[164:167], v[114:117], v[66:81]
	v_cndmask_b32_e32 v162, v194, v90, vcc
	v_add_u32_e32 v90, 0xf1, v199
	v_cmp_lt_i32_e32 vcc, v90, v150
	v_exp_f32_e64 v90, -|v162|
	v_add_u32_e32 v167, 0xf2, v199
	v_cndmask_b32_e32 v163, v194, v91, vcc
	v_exp_f32_e64 v91, -|v163|
	v_max_f32_e32 v171, 0, v89
	v_cmp_lt_i32_e32 vcc, v167, v150
	v_add_f32_e64 v164, v170, v168
	v_add_f32_e64 v165, v171, v169
	v_add_f32_e64 v90, v90, 1.0
	v_add_f32_e64 v91, v91, 1.0
	v_cndmask_b32_e32 v168, v194, v92, vcc
	v_add_u32_e32 v92, 0xf3, v199
	v_cmp_lt_i32_e32 vcc, v92, v150
	v_log_f32_e32 v90, v90
	v_log_f32_e32 v91, v91
	v_cndmask_b32_e32 v169, v194, v93, vcc
	v_exp_f32_e64 v92, -|v168|
	v_exp_f32_e64 v93, -|v169|
	v_max_f32_e32 v166, 0, v162
	v_max_f32_e32 v167, 0, v163
	v_add_f32_e64 v170, v166, v90
	v_add_f32_e64 v171, v167, v91
	v_add_f32_e64 v90, v92, 1.0
	v_add_f32_e64 v91, v93, 1.0
	v_log_f32_e32 v92, v90
	v_max_f32_e32 v166, 0, v168
	v_add_u32_e32 v90, 0xf8, v199
	v_log_f32_e32 v93, v91
	v_cmp_lt_i32_e32 vcc, v90, v150
	v_add_u32_e32 v91, 0xf9, v199
	v_max_f32_e32 v167, 0, v169
	v_cndmask_b32_e32 v90, v194, v94, vcc
	v_cmp_lt_i32_e32 vcc, v91, v150
	v_exp_f32_e64 v94, -|v90|
	v_add_f32_e64 v174, v166, v92
	v_add_f32_e64 v175, v167, v93
	v_cndmask_b32_e32 v91, v194, v95, vcc
	v_exp_f32_e64 v95, -|v91|
	s_waitcnt lgkmcnt(2)
	v_mfma_f32_32x32x16_bf16 v[66:81], v[180:183], v[118:121], v[66:81]
	v_max_f32_e32 v167, 0, v91
	v_add_f32_e64 v92, v94, 1.0
	v_add_f32_e64 v93, v95, 1.0
	v_log_f32_e32 v94, v92
	v_max_f32_e32 v166, 0, v90
	v_add_u32_e32 v92, 0xfa, v199
	v_log_f32_e32 v95, v93
	v_cmp_lt_i32_e32 vcc, v92, v150
	v_add_u32_e32 v93, 0xfb, v199
	s_nop 0
	v_cndmask_b32_e32 v92, v194, v96, vcc
	v_cmp_lt_i32_e32 vcc, v93, v150
	v_exp_f32_e64 v96, -|v92|
	v_add_f32_e64 v172, v166, v94
	v_add_f32_e64 v173, v167, v95
	v_cndmask_b32_e32 v93, v194, v97, vcc
	v_exp_f32_e64 v97, -|v93|
	v_add_f32_e64 v182, v174, v175
	v_add_f32_e64 v183, v170, v171
	v_add_f32_e64 v94, v96, 1.0
	v_add_f32_e64 v95, v97, 1.0
	v_log_f32_e32 v94, v94
	v_log_f32_e32 v95, v95
	v_max_f32_e32 v96, 0, v92
	v_max_f32_e32 v97, 0, v93
	v_add_f32_e64 v94, v96, v94
	v_add_f32_e64 v95, v97, v95
	v_mov_b32_e32 v96, v160
	v_and_b32_e32 v160, 64, v195
	v_add_f32_e64 v180, v171, v182
	v_add_f32_e64 v181, v183, v182
	v_mov_b32_e32 v170, v94
	v_xor_b32_e32 v94, 32, v195
	v_add_u32_e32 v160, 64, v160
	s_waitcnt lgkmcnt(1)
	v_mfma_f32_32x32x16_bf16 v[66:81], v[184:187], v[122:125], v[66:81]
	v_add_f32_e64 v170, v170, v95
	v_add_f32_e64 v171, v172, v173
	v_cmp_lt_i32_e32 vcc, v94, v160
	s_nop 1
	v_cndmask_b32_e32 v94, v195, v94, vcc
	v_add_f32_e64 v178, v164, v165
	v_add_f32_e64 v179, v176, v177
	v_add_f32_e64 v172, v173, v170
	v_add_f32_e64 v173, v171, v170
	v_lshlrev_b32_e32 v164, 2, v94
	v_add_f32_e64 v166, v96, v161
	v_add_f32_e64 v167, v188, v189
	v_mov_b32_e32 v96, v189
	ds_bpermute_b32 v189, v164, v181
	ds_bpermute_b32 v188, v164, v173
	v_add_f32_e64 v176, v177, v178
	v_add_f32_e64 v177, v179, v178
	v_add_f32_e64 v96, v96, v166
	v_add_f32_e64 v97, v167, v166
	ds_bpermute_b32 v160, v164, v177
	ds_bpermute_b32 v192, v164, v97
	s_waitcnt lgkmcnt(2)
	v_add_f32_e64 v190, v173, v188
	v_add_f32_e64 v191, v181, v189
	v_mfma_f32_32x32x16_bf16 v[66:81], v[200:203], v[126:129], v[66:81]
	v_add_f32_e64 v186, v190, v191
	v_add_f32_e64 v187, v191, v190
	s_waitcnt lgkmcnt(1)
	v_add_f32_e32 v185, v177, v160
	s_waitcnt lgkmcnt(0)
	v_add_f32_e64 v184, v97, v192
	v_add_f32_e64 v185, v185, v186
	s_nop 0
	v_add_f32_e32 v94, v184, v185
	v_add_f32_e32 v94, v0, v94
	v_cmp_le_f32_e32 vcc, s49, v94
	s_cmp_eq_u64 vcc, exec
	s_cbranch_scc1 .LBB0_592
	v_add_u32_e32 v167, 0xc0, v199
	v_cmp_lt_i32_e32 vcc, v167, v150
	v_add_u32_e32 v167, 0xc1, v199
	v_add_f32_e32 v179, 0, v94
	v_cndmask_b32_e32 v66, v194, v66, vcc
	v_cmp_lt_i32_e32 vcc, v167, v150
	v_exp_f32_e64 v200, -|v66|
	v_max_f32_e32 v167, v66, v66
	v_cndmask_b32_e32 v67, v194, v67, vcc
	v_exp_f32_e64 v201, -|v67|
	v_max_f32_e32 v202, 0, v167
	v_add_u32_e32 v167, 0xc2, v199
	v_cmp_lt_i32_e32 vcc, v167, v150
	v_add_u32_e32 v167, 0xc3, v199
	v_add_f32_e64 v200, v200, 1.0
	v_add_f32_e64 v201, v201, 1.0
	v_cndmask_b32_e32 v68, v194, v68, vcc
	v_cmp_lt_i32_e32 vcc, v167, v150
	v_log_f32_e32 v200, v200
	v_log_f32_e32 v201, v201
	v_cndmask_b32_e32 v69, v194, v69, vcc
	v_exp_f32_e64 v204, -|v68|
	v_exp_f32_e64 v205, -|v69|
	v_max_f32_e32 v203, 0, v67
	v_add_f32_e64 v200, v202, v200
	v_add_f32_e64 v201, v203, v201
	v_add_f32_e64 v202, v204, 1.0
	v_add_f32_e64 v203, v205, 1.0
	v_max_f32_e32 v204, 0, v68
	v_add_u32_e32 v167, 0xc8, v199
	v_cmp_lt_i32_e32 vcc, v167, v150
	v_add_u32_e32 v167, 0xc9, v199
	v_log_f32_e32 v202, v202
	v_cndmask_b32_e32 v70, v194, v70, vcc
	v_cmp_lt_i32_e32 vcc, v167, v150
	v_log_f32_e32 v203, v203
	v_exp_f32_e64 v206, -|v70|
	v_cndmask_b32_e32 v71, v194, v71, vcc
	v_exp_f32_e64 v207, -|v71|
	v_max_f32_e32 v205, 0, v69
	v_add_f32_e64 v202, v204, v202
	v_add_f32_e64 v203, v205, v203
	v_add_f32_e64 v204, v206, 1.0
	v_add_f32_e64 v205, v207, 1.0
	v_max_f32_e32 v206, 0, v70
	v_add_u32_e32 v167, 0xca, v199
	v_cmp_lt_i32_e32 vcc, v167, v150
	v_add_u32_e32 v167, 0xcb, v199
	v_log_f32_e32 v204, v204
	v_cndmask_b32_e32 v72, v194, v72, vcc
	v_cmp_lt_i32_e32 vcc, v167, v150
	v_log_f32_e32 v205, v205
	v_exp_f32_e64 v208, -|v72|
	v_cndmask_b32_e32 v73, v194, v73, vcc
	v_exp_f32_e64 v209, -|v73|
	v_max_f32_e32 v207, 0, v71
	v_add_f32_e64 v204, v206, v204
	v_add_f32_e64 v205, v207, v205
	v_add_f32_e64 v206, v208, 1.0
	v_add_f32_e64 v207, v209, 1.0
	v_max_f32_e32 v208, 0, v72
	v_add_u32_e32 v167, 0xd0, v199
	v_cmp_lt_i32_e32 vcc, v167, v150
	v_add_u32_e32 v167, 0xd1, v199
	v_log_f32_e32 v206, v206
	v_cndmask_b32_e32 v74, v194, v74, vcc
	v_cmp_lt_i32_e32 vcc, v167, v150
	v_log_f32_e32 v207, v207
	v_exp_f32_e64 v210, -|v74|
	v_cndmask_b32_e32 v75, v194, v75, vcc
	v_exp_f32_e64 v211, -|v75|
	v_max_f32_e32 v209, 0, v73
	v_add_f32_e64 v206, v208, v206
	v_add_f32_e64 v207, v209, v207
	v_add_f32_e64 v208, v210, 1.0
	v_add_f32_e64 v209, v211, 1.0
	v_max_f32_e32 v210, 0, v74
	v_add_u32_e32 v167, 0xd2, v199
	v_cmp_lt_i32_e32 vcc, v167, v150
	v_add_u32_e32 v167, 0xd3, v199
	v_log_f32_e32 v208, v208
	v_cndmask_b32_e32 v76, v194, v76, vcc
	v_cmp_lt_i32_e32 vcc, v167, v150
	v_log_f32_e32 v209, v209
	v_exp_f32_e64 v212, -|v76|
	v_cndmask_b32_e32 v77, v194, v77, vcc
	v_exp_f32_e64 v213, -|v77|
	v_max_f32_e32 v211, 0, v75
	v_add_f32_e64 v208, v210, v208
	v_add_f32_e64 v209, v211, v209
	v_add_f32_e64 v210, v212, 1.0
	v_add_f32_e64 v211, v213, 1.0
	v_max_f32_e32 v212, 0, v76
	v_add_u32_e32 v167, 0xd8, v199
	v_cmp_lt_i32_e32 vcc, v167, v150
	v_add_u32_e32 v167, 0xd9, v199
	v_log_f32_e32 v210, v210
	v_cndmask_b32_e32 v78, v194, v78, vcc
	v_cmp_lt_i32_e32 vcc, v167, v150
	v_log_f32_e32 v211, v211
	v_exp_f32_e64 v214, -|v78|
	v_cndmask_b32_e32 v79, v194, v79, vcc
	v_exp_f32_e64 v215, -|v79|
	v_max_f32_e32 v213, 0, v77
	v_add_f32_e64 v210, v212, v210
	v_add_f32_e64 v211, v213, v211
	v_add_f32_e64 v212, v214, 1.0
	v_add_f32_e64 v213, v215, 1.0
	v_max_f32_e32 v214, 0, v78
	v_add_u32_e32 v167, 0xda, v199
	v_cmp_lt_i32_e32 vcc, v167, v150
	v_add_u32_e32 v167, 0xdb, v199
	v_log_f32_e32 v212, v212
	v_cndmask_b32_e32 v80, v194, v80, vcc
	v_cmp_lt_i32_e32 vcc, v167, v150
	v_log_f32_e32 v213, v213
	v_exp_f32_e64 v216, -|v80|
	v_cndmask_b32_e32 v81, v194, v81, vcc
	v_exp_f32_e64 v217, -|v81|
	v_max_f32_e32 v215, 0, v79
	v_add_f32_e64 v212, v214, v212
	v_add_f32_e64 v213, v215, v213
	v_add_f32_e64 v214, v216, 1.0
	v_add_f32_e64 v215, v217, 1.0
	v_log_f32_e32 v214, v214
	v_log_f32_e32 v215, v215
	v_max_f32_e32 v216, 0, v80
	v_max_f32_e32 v217, 0, v81
	v_add_f32_e64 v214, v216, v214
	v_add_f32_e64 v215, v217, v215
	v_add_f32_e64 v220, v210, v211
	v_add_f32_e64 v221, v208, v209
	v_add_f32_e64 v222, v214, v215
	v_add_f32_e64 v223, v212, v213
	v_add_f32_e64 v208, v209, v220
	v_add_f32_e64 v209, v221, v220
	v_add_f32_e64 v212, v213, v222
	v_add_f32_e64 v213, v223, v222
	ds_bpermute_b32 v226, v164, v209
	ds_bpermute_b32 v227, v164, v213
	v_add_f32_e64 v216, v202, v203
	v_add_f32_e64 v217, v200, v201
	v_add_f32_e64 v218, v206, v207
	v_add_f32_e64 v219, v204, v205
	v_mov_b32_e32 v221, v211
	v_add_f32_e64 v200, v201, v216
	v_add_f32_e64 v201, v217, v216
	v_add_f32_e64 v204, v205, v218
	v_add_f32_e64 v205, v219, v218
	s_waitcnt lgkmcnt(0)
	v_add_f32_e64 v210, v209, v226
	v_add_f32_e64 v211, v213, v227
	ds_bpermute_b32 v202, v164, v201
	ds_bpermute_b32 v167, v164, v205
	v_cndmask_b32_e64 v164, 0, v226, s[4:5]
	v_add_f32_e32 v184, v94, v211
	v_add_f32_e32 v164, v164, v184
	v_add_f32_e64 v220, v220, v164
	v_add_f32_e64 v221, v221, v164
	s_waitcnt lgkmcnt(0)
	v_cndmask_b32_e64 v174, 0, v167, s[4:5]
	v_add_f32_e64 v76, v76, -v220
	v_add_f32_e64 v77, v77, -v221
	v_exp_f32_e32 v184, v77
	v_exp_f32_e32 v187, v76
	v_add_f32_e64 v76, v209, v164
	v_add_f32_e64 v77, v208, v164
	v_add_f32_e64 v74, v74, -v76
	v_add_f32_e64 v75, v75, -v77
	v_exp_f32_e32 v77, v75
	v_exp_f32_e32 v164, v74
	v_add_f32_e64 v74, v210, v211
	v_add_f32_e64 v75, v211, v210
	v_cndmask_b32_e64 v171, 0, v202, s[4:5]
	v_add_f32_e32 v75, v94, v74
	v_add_f32_e32 v76, v174, v75
	v_add_f32_e64 v206, v218, v76
	v_add_f32_e64 v207, v207, v76
	v_add_f32_e64 v72, v72, -v206
	v_add_f32_e64 v73, v73, -v207
	v_cndmask_b32_e64 v183, 0, v227, s[4:5]
	v_exp_f32_e32 v174, v73
	v_exp_f32_e32 v191, v72
	v_add_f32_e64 v72, v205, v76
	v_add_f32_e64 v73, v204, v76
	v_add_f32_e64 v70, v70, -v72
	v_add_f32_e64 v71, v71, -v73
	v_exp_f32_e32 v73, v71
	v_exp_f32_e32 v76, v70
	v_add_f32_e32 v71, v205, v167
	v_add_f32_e64 v70, v201, v202
	v_add_f32_e64 v71, v71, v74
	s_nop 0
	v_add_f32_e32 v72, v94, v71
	v_add_f32_e32 v72, v171, v72
	v_add_f32_e64 v74, v216, v72
	v_add_f32_e64 v75, v203, v72
	s_nop 0
	v_add_f32_e64 v68, v68, -v74
	v_add_f32_e64 v69, v69, -v75
	s_nop 0
	v_exp_f32_e32 v74, v69
	v_exp_f32_e32 v75, v68
	v_add_f32_e64 v68, v201, v72
	v_add_f32_e64 v69, v200, v72
	v_add_f32_e64 v66, v66, -v68
	v_add_f32_e64 v67, v67, -v69
	s_nop 0
	v_exp_f32_e32 v167, v66
	v_add_f32_e32 v66, v179, v183
	v_exp_f32_e32 v72, v67
	v_add_f32_e64 v68, v213, v66
	v_add_f32_e64 v69, v212, v66
	v_add_f32_e64 v67, v215, v66
	v_add_f32_e64 v66, v222, v66
	v_add_f32_e64 v68, v78, -v68
	v_add_f32_e64 v69, v79, -v69
	v_add_f32_e64 v66, v80, -v66
	v_add_f32_e64 v67, v81, -v67
	v_exp_f32_e32 v68, v68
	v_exp_f32_e32 v69, v69
	v_exp_f32_e32 v78, v66
	v_exp_f32_e32 v79, v67
	v_add_f32_e32 v66, v70, v71
	v_add_f32_e32 v94, v94, v66
	v_cvt_pk_bf16_f32 v70, v167, v72
	v_cvt_pk_bf16_f32 v71, v75, v74
	v_cvt_pk_bf16_f32 v72, v76, v73
	v_cvt_pk_bf16_f32 v73, v191, v174
	v_cvt_pk_bf16_f32 v66, v164, v77
	v_cvt_pk_bf16_f32 v67, v187, v184
	v_cvt_pk_bf16_f32 v68, v68, v69
	v_cvt_pk_bf16_f32 v69, v78, v79
	s_branch .LBB0_593

.LBB0_593:
	v_cndmask_b32_e64 v74, 0, v189, s[4:5]
	v_add_f32_e32 v75, v0, v190
	v_add_f32_e32 v74, v74, v75
	v_add_f32_e64 v76, v182, v74
	v_add_f32_e64 v77, v175, v74
	v_add_f32_e64 v75, v180, v74
	v_add_f32_e64 v74, v181, v74
	v_add_f32_e64 v74, v162, -v74
	v_add_f32_e64 v75, v163, -v75
	v_cndmask_b32_e64 v79, 0, v160, s[4:5]
	v_exp_f32_e32 v163, v74
	v_add_f32_e32 v74, v0, v186
	v_add_f32_e64 v76, v168, -v76
	v_add_f32_e64 v77, v169, -v77
	v_add_f32_e32 v74, v79, v74
	v_exp_f32_e32 v168, v77
	v_exp_f32_e32 v169, v76
	v_exp_f32_e32 v162, v75
	v_add_f32_e64 v76, v178, v74
	v_add_f32_e64 v77, v165, v74
	v_add_f32_e64 v75, v176, v74
	v_add_f32_e64 v74, v177, v74
	v_add_f32_e64 v76, v88, -v76
	v_add_f32_e64 v77, v89, -v77
	v_add_f32_e64 v74, v86, -v74
	v_add_f32_e64 v75, v87, -v75
	v_mov_b32_e32 v167, v161
	v_add_u32_e32 v161, s42, v198
	v_exp_f32_e32 v88, v77
	v_exp_f32_e32 v89, v76
	v_exp_f32_e32 v165, v75
	v_exp_f32_e32 v174, v74
	ds_read_b128 v[74:77], v161 offset:17408
	v_cndmask_b32_e64 v78, 0, v192, s[4:5]
	v_add_f32_e32 v160, 0, v0
	v_add_f32_e32 v0, v0, v185
	v_add_f32_e32 v0, v78, v0
	v_add_f32_e64 v78, v166, v0
	v_add_f32_e64 v79, v167, v0
	v_cndmask_b32_e64 v164, 0, v188, s[4:5]
	v_add_f32_e64 v78, v84, -v78
	v_add_f32_e64 v79, v85, -v79
	v_exp_f32_e32 v84, v79
	v_exp_f32_e32 v85, v78
	v_add_f32_e64 v78, v97, v0
	v_add_f32_e64 v79, v96, v0
	v_add_f32_e64 v82, v82, -v78
	v_add_f32_e64 v83, v83, -v79
	ds_read_b128 v[78:81], v161 offset:17440
	s_waitcnt lgkmcnt(1)
	v_mfma_f32_32x32x16_bf16 v[50:65], v[74:77], v[70:73], v[50:65]
	v_add_f32_e32 v0, v160, v164
	v_add_f32_e64 v74, v0, v173
	v_add_f32_e64 v75, v0, v172
	v_exp_f32_e32 v96, v83
	v_exp_f32_e32 v97, v82
	v_add_f32_e64 v82, v90, -v74
	v_add_f32_e64 v83, v91, -v75
	ds_read_b128 v[74:77], v161 offset:17472
	v_exp_f32_e32 v90, v82
	s_waitcnt lgkmcnt(1)
	v_mfma_f32_32x32x16_bf16 v[50:65], v[78:81], v[66:69], v[50:65]
	v_exp_f32_e32 v91, v83
	v_cvt_pk_bf16_f32 v78, v97, v96
	v_cvt_pk_bf16_f32 v79, v85, v84
	v_cvt_pk_bf16_f32 v80, v174, v165
	v_cvt_pk_bf16_f32 v81, v89, v88
	ds_read_b128 v[82:85], v161 offset:17504
	v_add_f32_e64 v86, v0, v170
	v_add_f32_e64 v87, v0, v95
	s_waitcnt lgkmcnt(1)
	v_mfma_f32_32x32x16_bf16 v[50:65], v[74:77], v[78:81], v[50:65]
	v_add_f32_e64 v74, v92, -v86
	v_add_f32_e64 v75, v93, -v87
	v_cvt_pk_bf16_f32 v76, v90, v91
	v_exp_f32_e32 v0, v74
	v_exp_f32_e32 v77, v75
	v_cvt_pk_bf16_f32 v74, v163, v162
	v_cvt_pk_bf16_f32 v75, v169, v168
	v_cmp_le_f32_e32 vcc, s49, v94
	v_cvt_pk_bf16_f32 v77, v0, v77
	s_cmp_eq_u64 vcc, exec
	s_cselect_b64 s[42:43], -1, 0
	s_waitcnt lgkmcnt(0)
	v_mfma_f32_32x32x16_bf16 v[50:65], v[82:85], v[74:77], v[50:65]
	ds_read_b128 v[82:85], v161 offset:22016
	ds_read_b128 v[86:89], v161 offset:22048
	v_mov_b32_e32 v0, v94
	s_waitcnt lgkmcnt(1)
	v_mfma_f32_32x32x16_bf16 v[34:49], v[82:85], v[70:73], v[34:49]
	s_waitcnt lgkmcnt(0)
	v_mfma_f32_32x32x16_bf16 v[34:49], v[86:89], v[66:69], v[34:49]
	ds_read_b128 v[82:85], v161 offset:22080
	ds_read_b128 v[86:89], v161 offset:22112
	s_waitcnt lgkmcnt(1)
	v_mfma_f32_32x32x16_bf16 v[34:49], v[82:85], v[78:81], v[34:49]
	s_waitcnt lgkmcnt(0)
	v_mfma_f32_32x32x16_bf16 v[34:49], v[86:89], v[74:77], v[34:49]
	ds_read_b128 v[82:85], v161 offset:26624
	ds_read_b128 v[86:89], v161 offset:26656
	s_waitcnt lgkmcnt(1)
	v_mfma_f32_32x32x16_bf16 v[18:33], v[82:85], v[70:73], v[18:33]
	s_waitcnt lgkmcnt(0)
	v_mfma_f32_32x32x16_bf16 v[18:33], v[86:89], v[66:69], v[18:33]
	ds_read_b128 v[82:85], v161 offset:26688
	ds_read_b128 v[86:89], v161 offset:26720
	s_waitcnt lgkmcnt(1)
	v_mfma_f32_32x32x16_bf16 v[18:33], v[82:85], v[78:81], v[18:33]
	s_waitcnt lgkmcnt(0)
	v_mfma_f32_32x32x16_bf16 v[18:33], v[86:89], v[74:77], v[18:33]
	ds_read_b128 v[82:85], v161 offset:31232
	ds_read_b128 v[86:89], v161 offset:31264
	s_waitcnt lgkmcnt(1)
	v_mfma_f32_32x32x16_bf16 v[2:17], v[82:85], v[70:73], v[2:17]
	s_waitcnt lgkmcnt(0)
	v_mfma_f32_32x32x16_bf16 v[2:17], v[86:89], v[66:69], v[2:17]
	ds_read_b128 v[66:69], v161 offset:31296
	ds_read_b128 v[70:73], v161 offset:31328
	s_waitcnt lgkmcnt(1)
	v_mfma_f32_32x32x16_bf16 v[2:17], v[66:69], v[78:81], v[2:17]
	s_waitcnt lgkmcnt(0)
	v_mfma_f32_32x32x16_bf16 v[2:17], v[70:73], v[74:77], v[2:17]

.LBB0_671:
	s_ashr_i32 s51, s50, 31
	s_lshl_b64 s[52:53], s[50:51], 20
	s_add_u32 s52, s10, s52
	s_addc_u32 s53, s11, s53
	s_and_b64 s[54:55], s[6:7], exec
	s_cselect_b32 s51, s53, s61
	s_cselect_b32 s57, s52, s60
	s_ashr_i32 s49, s48, 31
	s_lshl_b64 s[54:55], s[48:49], 20
	s_add_u32 s54, s34, s54
	s_addc_u32 s55, s35, s55
	s_and_b64 s[64:65], s[6:7], exec
	s_cselect_b32 s49, s55, s63
	s_cselect_b32 s77, s54, s62
	s_add_u32 s60, s60, 0x80080
	s_addc_u32 s61, s61, 0
	s_add_u32 s81, s62, 0x100
	v_mov_b32_e32 v0, 0
	s_addc_u32 s82, s63, 0
	s_mov_b32 s83, -2
	s_waitcnt lgkmcnt(0)
	v_mov_b32_e32 v1, v0
	v_mov_b32_e32 v2, v0
	v_mov_b32_e32 v3, v0
	v_mov_b32_e32 v4, v0
	v_mov_b32_e32 v5, v0
	v_mov_b32_e32 v6, v0
	v_mov_b32_e32 v7, v0
	v_mov_b32_e32 v16, v0
	v_mov_b32_e32 v17, v0
	v_mov_b32_e32 v18, v0
	v_mov_b32_e32 v19, v0
	v_mov_b32_e32 v20, v0
	v_mov_b32_e32 v21, v0
	v_mov_b32_e32 v22, v0
	v_mov_b32_e32 v23, v0
	v_mov_b32_e32 v32, v0
	v_mov_b32_e32 v33, v0
	v_mov_b32_e32 v34, v0
	v_mov_b32_e32 v35, v0
	v_mov_b32_e32 v36, v0
	v_mov_b32_e32 v37, v0
	v_mov_b32_e32 v38, v0
	v_mov_b32_e32 v39, v0
	v_mov_b32_e32 v48, v0
	v_mov_b32_e32 v49, v0
	v_mov_b32_e32 v50, v0
	v_mov_b32_e32 v51, v0
	v_mov_b32_e32 v52, v0
	v_mov_b32_e32 v53, v0
	v_mov_b32_e32 v54, v0
	v_mov_b32_e32 v55, v0
	v_mov_b32_e32 v8, v0
	v_mov_b32_e32 v9, v0
	v_mov_b32_e32 v10, v0
	v_mov_b32_e32 v11, v0
	v_mov_b32_e32 v12, v0
	v_mov_b32_e32 v13, v0
	v_mov_b32_e32 v14, v0
	v_mov_b32_e32 v15, v0
	v_mov_b32_e32 v24, v0
	v_mov_b32_e32 v25, v0
	v_mov_b32_e32 v26, v0
	v_mov_b32_e32 v27, v0
	v_mov_b32_e32 v28, v0
	v_mov_b32_e32 v29, v0
	v_mov_b32_e32 v30, v0
	v_mov_b32_e32 v31, v0
	v_mov_b32_e32 v40, v0
	v_mov_b32_e32 v41, v0
	v_mov_b32_e32 v42, v0
	v_mov_b32_e32 v43, v0
	v_mov_b32_e32 v44, v0
	v_mov_b32_e32 v45, v0
	v_mov_b32_e32 v46, v0
	v_mov_b32_e32 v47, v0
	v_mov_b32_e32 v56, v0
	v_mov_b32_e32 v57, v0
	v_mov_b32_e32 v58, v0
	v_mov_b32_e32 v59, v0
	v_mov_b32_e32 v60, v0
	v_mov_b32_e32 v61, v0
	v_mov_b32_e32 v62, v0
	v_mov_b32_e32 v63, v0
	v_mov_b32_e32 v64, v0
	v_mov_b32_e32 v65, v0
	v_mov_b32_e32 v66, v0
	v_mov_b32_e32 v67, v0
	v_mov_b32_e32 v68, v0
	v_mov_b32_e32 v69, v0
	v_mov_b32_e32 v70, v0
	v_mov_b32_e32 v71, v0
	v_mov_b32_e32 v80, v0
	v_mov_b32_e32 v81, v0
	v_mov_b32_e32 v82, v0
	v_mov_b32_e32 v83, v0
	v_mov_b32_e32 v84, v0
	v_mov_b32_e32 v85, v0
	v_mov_b32_e32 v86, v0
	v_mov_b32_e32 v87, v0
	v_mov_b32_e32 v96, v0
	v_mov_b32_e32 v97, v0
	v_mov_b32_e32 v98, v0
	v_mov_b32_e32 v99, v0
	v_mov_b32_e32 v100, v0
	v_mov_b32_e32 v101, v0
	v_mov_b32_e32 v102, v0
	v_mov_b32_e32 v103, v0
	v_mov_b32_e32 v112, v0
	v_mov_b32_e32 v113, v0
	v_mov_b32_e32 v114, v0
	v_mov_b32_e32 v115, v0
	v_mov_b32_e32 v116, v0
	v_mov_b32_e32 v117, v0
	v_mov_b32_e32 v118, v0
	v_mov_b32_e32 v119, v0
	v_mov_b32_e32 v72, v0
	v_mov_b32_e32 v73, v0
	v_mov_b32_e32 v74, v0
	v_mov_b32_e32 v75, v0
	v_mov_b32_e32 v76, v0
	v_mov_b32_e32 v77, v0
	v_mov_b32_e32 v78, v0
	v_mov_b32_e32 v79, v0
	v_mov_b32_e32 v88, v0
	v_mov_b32_e32 v89, v0
	v_mov_b32_e32 v90, v0
	v_mov_b32_e32 v91, v0
	v_mov_b32_e32 v92, v0
	v_mov_b32_e32 v93, v0
	v_mov_b32_e32 v94, v0
	v_mov_b32_e32 v95, v0
	v_mov_b32_e32 v104, v0
	v_mov_b32_e32 v105, v0
	v_mov_b32_e32 v106, v0
	v_mov_b32_e32 v107, v0
	v_mov_b32_e32 v108, v0
	v_mov_b32_e32 v109, v0
	v_mov_b32_e32 v110, v0
	v_mov_b32_e32 v111, v0
	v_mov_b32_e32 v120, v0
	v_mov_b32_e32 v121, v0
	v_mov_b32_e32 v122, v0
	v_mov_b32_e32 v123, v0
	v_mov_b32_e32 v124, v0
	v_mov_b32_e32 v125, v0
	v_mov_b32_e32 v126, v0
	v_mov_b32_e32 v127, v0
	s_nop 0
	s_nop 0
	s_nop 0
.LBB0_672:
	ds_read_b128 v[144:147], v153
	ds_read_b128 v[158:161], v153 offset:1024
	ds_read_b128 v[162:165], v153 offset:2048
	ds_read_b128 v[166:169], v153 offset:3072
	ds_read_b128 v[170:173], v154
	ds_read_b128 v[174:177], v154 offset:1024
	ds_read_b128 v[178:181], v154 offset:2048
	ds_read_b128 v[182:185], v154 offset:3072
	s_add_u32 s62, s60, 0xfff80080
	s_addc_u32 s63, s61, -1
	s_cmp_eq_u32 s83, 28
	s_cselect_b32 s65, s51, s63
	s_cselect_b32 s64, s57, s62
	s_cselect_b32 s63, s49, s82
	s_cselect_b32 s62, s77, s81
	v_lshl_add_u64 v[148:149], s[60:61], 0, v[136:137]
	s_add_i32 m0, s59, 0xc000
	ds_read_b128 v[186:189], v155
	ds_read_b128 v[190:193], v155 offset:1024
	ds_read_b128 v[194:197], v155 offset:2048
	ds_read_b128 v[198:201], v155 offset:3072
	ds_read_b128 v[202:205], v155 offset:4096
	ds_read_b128 v[206:209], v155 offset:5120
	ds_read_b128 v[210:213], v155 offset:6144
	ds_read_b128 v[214:217], v155 offset:7168
	global_load_lds_dwordx4 v[148:149], off
	v_lshl_add_u64 v[148:149], s[60:61], 0, v[138:139]
	s_add_i32 m0, s59, 0xe000
	s_nop 0
	global_load_lds_dwordx4 v[148:149], off
	s_waitcnt vmcnt(8)
	s_waitcnt lgkmcnt(0)
	s_barrier
	s_setprio 1
	s_waitcnt lgkmcnt(0)
	v_mfma_f32_16x16x32_bf16 v[124:127], v[144:147], v[186:189], v[124:127]
	v_mfma_f32_16x16x32_bf16 v[120:123], v[162:165], v[186:189], v[120:123]
	v_mfma_f32_16x16x32_bf16 v[108:111], v[144:147], v[194:197], v[108:111]
	v_mfma_f32_16x16x32_bf16 v[104:107], v[162:165], v[194:197], v[104:107]
	v_mfma_f32_16x16x32_bf16 v[92:95], v[144:147], v[202:205], v[92:95]
	v_mfma_f32_16x16x32_bf16 v[88:91], v[162:165], v[202:205], v[88:91]
	v_mfma_f32_16x16x32_bf16 v[76:79], v[144:147], v[210:213], v[76:79]
	v_mfma_f32_16x16x32_bf16 v[72:75], v[162:165], v[210:213], v[72:75]
	v_mfma_f32_16x16x32_bf16 v[124:127], v[158:161], v[190:193], v[124:127]
	v_mfma_f32_16x16x32_bf16 v[120:123], v[166:169], v[190:193], v[120:123]
	v_mfma_f32_16x16x32_bf16 v[108:111], v[158:161], v[198:201], v[108:111]
	v_mfma_f32_16x16x32_bf16 v[104:107], v[166:169], v[198:201], v[104:107]
	v_mfma_f32_16x16x32_bf16 v[92:95], v[158:161], v[206:209], v[92:95]
	v_mfma_f32_16x16x32_bf16 v[88:91], v[166:169], v[206:209], v[88:91]
	v_mfma_f32_16x16x32_bf16 v[76:79], v[158:161], v[214:217], v[76:79]
	v_mfma_f32_16x16x32_bf16 v[72:75], v[166:169], v[214:217], v[72:75]
	s_setprio 0
	s_setprio 1
	v_mfma_f32_16x16x32_bf16 v[116:119], v[170:173], v[186:189], v[116:119]
	v_mfma_f32_16x16x32_bf16 v[112:115], v[178:181], v[186:189], v[112:115]
	v_mfma_f32_16x16x32_bf16 v[100:103], v[170:173], v[194:197], v[100:103]
	v_mfma_f32_16x16x32_bf16 v[96:99], v[178:181], v[194:197], v[96:99]
	v_mfma_f32_16x16x32_bf16 v[84:87], v[170:173], v[202:205], v[84:87]
	v_mfma_f32_16x16x32_bf16 v[80:83], v[178:181], v[202:205], v[80:83]
	v_mfma_f32_16x16x32_bf16 v[68:71], v[170:173], v[210:213], v[68:71]
	v_mfma_f32_16x16x32_bf16 v[64:67], v[178:181], v[210:213], v[64:67]
	v_mfma_f32_16x16x32_bf16 v[116:119], v[174:177], v[190:193], v[116:119]
	v_mfma_f32_16x16x32_bf16 v[112:115], v[182:185], v[190:193], v[112:115]
	v_mfma_f32_16x16x32_bf16 v[100:103], v[174:177], v[198:201], v[100:103]
	v_mfma_f32_16x16x32_bf16 v[96:99], v[182:185], v[198:201], v[96:99]
	v_mfma_f32_16x16x32_bf16 v[84:87], v[174:177], v[206:209], v[84:87]
	v_mfma_f32_16x16x32_bf16 v[80:83], v[182:185], v[206:209], v[80:83]
	v_mfma_f32_16x16x32_bf16 v[68:71], v[174:177], v[214:217], v[68:71]
	v_mfma_f32_16x16x32_bf16 v[64:67], v[182:185], v[214:217], v[64:67]
	s_setprio 0
	s_barrier
	s_add_i32 s84, s75, s3
	v_lshl_add_u64 v[148:149], s[62:63], 0, v[130:131]
	s_mov_b32 m0, s84
	ds_read_b128 v[186:189], v155 offset:16384
	ds_read_b128 v[190:193], v155 offset:17408
	ds_read_b128 v[194:197], v155 offset:18432
	ds_read_b128 v[198:201], v155 offset:19456
	ds_read_b128 v[202:205], v155 offset:20480
	ds_read_b128 v[206:209], v155 offset:21504
	ds_read_b128 v[210:213], v155 offset:22528
	ds_read_b128 v[214:217], v155 offset:23552
	global_load_lds_dwordx4 v[148:149], off
	s_add_i32 m0, s84, 0x2000
	s_add_u32 s84, s62, 0x80000
	v_lshl_add_u64 v[218:219], s[62:63], 0, v[134:135]
	s_addc_u32 s85, s63, 0
	s_add_i32 s86, s76, s3
	global_load_lds_dwordx4 v[218:219], off
	v_lshl_add_u64 v[220:221], s[84:85], 0, v[130:131]
	s_mov_b32 m0, s86
	v_lshl_add_u64 v[222:223], s[64:65], 0, v[132:133]
	global_load_lds_dwordx4 v[220:221], off
	v_lshl_add_u64 v[220:221], s[84:85], 0, v[134:135]
	s_add_i32 m0, s86, 0x2000
	s_nop 0
	global_load_lds_dwordx4 v[220:221], off
	v_lshl_add_u64 v[220:221], s[64:65], 0, v[128:129]
	s_mov_b32 m0, s59
	s_nop 0
	global_load_lds_dwordx4 v[220:221], off
	s_mov_b32 m0, s66
	s_nop 0
	global_load_lds_dwordx4 v[222:223], off
	s_waitcnt vmcnt(8)
	s_waitcnt lgkmcnt(0)
	s_barrier
	s_setprio 1
	s_waitcnt lgkmcnt(0)
	v_mfma_f32_16x16x32_bf16 v[60:63], v[144:147], v[186:189], v[60:63]
	v_mfma_f32_16x16x32_bf16 v[56:59], v[162:165], v[186:189], v[56:59]
	v_mfma_f32_16x16x32_bf16 v[44:47], v[144:147], v[194:197], v[44:47]
	v_mfma_f32_16x16x32_bf16 v[40:43], v[162:165], v[194:197], v[40:43]
	v_mfma_f32_16x16x32_bf16 v[28:31], v[144:147], v[202:205], v[28:31]
	v_mfma_f32_16x16x32_bf16 v[24:27], v[162:165], v[202:205], v[24:27]
	v_mfma_f32_16x16x32_bf16 v[12:15], v[144:147], v[210:213], v[12:15]
	v_mfma_f32_16x16x32_bf16 v[8:11], v[162:165], v[210:213], v[8:11]
	v_mfma_f32_16x16x32_bf16 v[60:63], v[158:161], v[190:193], v[60:63]
	v_mfma_f32_16x16x32_bf16 v[56:59], v[166:169], v[190:193], v[56:59]
	v_mfma_f32_16x16x32_bf16 v[44:47], v[158:161], v[198:201], v[44:47]
	v_mfma_f32_16x16x32_bf16 v[40:43], v[166:169], v[198:201], v[40:43]
	v_mfma_f32_16x16x32_bf16 v[28:31], v[158:161], v[206:209], v[28:31]
	v_mfma_f32_16x16x32_bf16 v[24:27], v[166:169], v[206:209], v[24:27]
	v_mfma_f32_16x16x32_bf16 v[12:15], v[158:161], v[214:217], v[12:15]
	v_mfma_f32_16x16x32_bf16 v[8:11], v[166:169], v[214:217], v[8:11]
	s_setprio 0
	s_setprio 1
	v_mfma_f32_16x16x32_bf16 v[52:55], v[170:173], v[186:189], v[52:55]
	v_mfma_f32_16x16x32_bf16 v[48:51], v[178:181], v[186:189], v[48:51]
	v_mfma_f32_16x16x32_bf16 v[36:39], v[170:173], v[194:197], v[36:39]
	v_mfma_f32_16x16x32_bf16 v[32:35], v[178:181], v[194:197], v[32:35]
	v_mfma_f32_16x16x32_bf16 v[20:23], v[170:173], v[202:205], v[20:23]
	v_mfma_f32_16x16x32_bf16 v[16:19], v[178:181], v[202:205], v[16:19]
	v_mfma_f32_16x16x32_bf16 v[4:7], v[170:173], v[210:213], v[4:7]
	v_mfma_f32_16x16x32_bf16 v[0:3], v[178:181], v[210:213], v[0:3]
	v_mfma_f32_16x16x32_bf16 v[52:55], v[174:177], v[190:193], v[52:55]
	v_mfma_f32_16x16x32_bf16 v[48:51], v[182:185], v[190:193], v[48:51]
	v_mfma_f32_16x16x32_bf16 v[36:39], v[174:177], v[198:201], v[36:39]
	v_mfma_f32_16x16x32_bf16 v[32:35], v[182:185], v[198:201], v[32:35]
	v_mfma_f32_16x16x32_bf16 v[20:23], v[174:177], v[206:209], v[20:23]
	v_mfma_f32_16x16x32_bf16 v[16:19], v[182:185], v[206:209], v[16:19]
	v_mfma_f32_16x16x32_bf16 v[4:7], v[174:177], v[214:217], v[4:7]
	v_mfma_f32_16x16x32_bf16 v[0:3], v[182:185], v[214:217], v[0:3]
	s_setprio 0
	s_barrier
	s_add_i32 s84, 0, 0x18000
	v_add_u32_e32 v157, s84, v151
	s_add_i32 s85, 0, 0x1c000
	ds_read_b128 v[144:147], v157
	ds_read_b128 v[158:161], v157 offset:1024
	ds_read_b128 v[162:165], v157 offset:2048
	ds_read_b128 v[166:169], v157 offset:3072
	v_add_u32_e32 v157, s85, v151
	ds_read_b128 v[170:173], v157
	ds_read_b128 v[174:177], v157 offset:1024
	ds_read_b128 v[178:181], v157 offset:2048
	ds_read_b128 v[182:185], v157 offset:3072
	s_add_u32 s64, s64, 0x80000
	s_addc_u32 s65, s65, 0
	s_mov_b32 m0, s67
	v_lshl_add_u64 v[228:229], s[64:65], 0, v[128:129]
	ds_read_b128 v[186:189], v155 offset:32768
	ds_read_b128 v[190:193], v155 offset:33792
	ds_read_b128 v[194:197], v155 offset:34816
	ds_read_b128 v[198:201], v155 offset:35840
	ds_read_b128 v[202:205], v155 offset:36864
	ds_read_b128 v[206:209], v155 offset:37888
	ds_read_b128 v[210:213], v155 offset:38912
	ds_read_b128 v[214:217], v155 offset:39936
	global_load_lds_dwordx4 v[228:229], off
	v_lshl_add_u64 v[228:229], s[64:65], 0, v[132:133]
	s_mov_b32 m0, s68
	s_nop 0
	global_load_lds_dwordx4 v[228:229], off
	s_waitcnt vmcnt(8)
	s_waitcnt lgkmcnt(0)
	s_barrier
	s_setprio 1
	s_waitcnt lgkmcnt(0)
	v_mfma_f32_16x16x32_bf16 v[124:127], v[144:147], v[186:189], v[124:127]
	v_mfma_f32_16x16x32_bf16 v[120:123], v[162:165], v[186:189], v[120:123]
	v_mfma_f32_16x16x32_bf16 v[108:111], v[144:147], v[194:197], v[108:111]
	v_mfma_f32_16x16x32_bf16 v[104:107], v[162:165], v[194:197], v[104:107]
	v_mfma_f32_16x16x32_bf16 v[92:95], v[144:147], v[202:205], v[92:95]
	v_mfma_f32_16x16x32_bf16 v[88:91], v[162:165], v[202:205], v[88:91]
	v_mfma_f32_16x16x32_bf16 v[76:79], v[144:147], v[210:213], v[76:79]
	v_mfma_f32_16x16x32_bf16 v[72:75], v[162:165], v[210:213], v[72:75]
	v_mfma_f32_16x16x32_bf16 v[124:127], v[158:161], v[190:193], v[124:127]
	v_mfma_f32_16x16x32_bf16 v[120:123], v[166:169], v[190:193], v[120:123]
	v_mfma_f32_16x16x32_bf16 v[108:111], v[158:161], v[198:201], v[108:111]
	v_mfma_f32_16x16x32_bf16 v[104:107], v[166:169], v[198:201], v[104:107]
	v_mfma_f32_16x16x32_bf16 v[92:95], v[158:161], v[206:209], v[92:95]
	v_mfma_f32_16x16x32_bf16 v[88:91], v[166:169], v[206:209], v[88:91]
	v_mfma_f32_16x16x32_bf16 v[76:79], v[158:161], v[214:217], v[76:79]
	v_mfma_f32_16x16x32_bf16 v[72:75], v[166:169], v[214:217], v[72:75]
	s_setprio 0
	s_setprio 1
	v_mfma_f32_16x16x32_bf16 v[116:119], v[170:173], v[186:189], v[116:119]
	v_mfma_f32_16x16x32_bf16 v[112:115], v[178:181], v[186:189], v[112:115]
	v_mfma_f32_16x16x32_bf16 v[100:103], v[170:173], v[194:197], v[100:103]
	v_mfma_f32_16x16x32_bf16 v[96:99], v[178:181], v[194:197], v[96:99]
	v_mfma_f32_16x16x32_bf16 v[84:87], v[170:173], v[202:205], v[84:87]
	v_mfma_f32_16x16x32_bf16 v[80:83], v[178:181], v[202:205], v[80:83]
	v_mfma_f32_16x16x32_bf16 v[68:71], v[170:173], v[210:213], v[68:71]
	v_mfma_f32_16x16x32_bf16 v[64:67], v[178:181], v[210:213], v[64:67]
	v_mfma_f32_16x16x32_bf16 v[116:119], v[174:177], v[190:193], v[116:119]
	v_mfma_f32_16x16x32_bf16 v[112:115], v[182:185], v[190:193], v[112:115]
	v_mfma_f32_16x16x32_bf16 v[100:103], v[174:177], v[198:201], v[100:103]
	v_mfma_f32_16x16x32_bf16 v[96:99], v[182:185], v[198:201], v[96:99]
	v_mfma_f32_16x16x32_bf16 v[84:87], v[174:177], v[206:209], v[84:87]
	v_mfma_f32_16x16x32_bf16 v[80:83], v[182:185], v[206:209], v[80:83]
	v_mfma_f32_16x16x32_bf16 v[68:71], v[174:177], v[214:217], v[68:71]
	v_mfma_f32_16x16x32_bf16 v[64:67], v[182:185], v[214:217], v[64:67]
	s_setprio 0
	s_barrier
	s_add_i32 s64, s84, s3
	v_lshl_add_u64 v[148:149], v[148:149], 0, s[16:17]
	s_mov_b32 m0, s64
	ds_read_b128 v[186:189], v155 offset:49152
	ds_read_b128 v[190:193], v155 offset:50176
	ds_read_b128 v[194:197], v155 offset:51200
	ds_read_b128 v[198:201], v155 offset:52224
	ds_read_b128 v[202:205], v155 offset:53248
	ds_read_b128 v[206:209], v155 offset:54272
	ds_read_b128 v[210:213], v155 offset:55296
	ds_read_b128 v[214:217], v155 offset:56320
	global_load_lds_dwordx4 v[148:149], off
	s_add_i32 m0, s64, 0x2000
	s_add_u32 s62, s62, 0x80080
	v_lshl_add_u64 v[148:149], v[218:219], 0, s[16:17]
	s_addc_u32 s63, s63, 0
	s_add_i32 s64, s85, s3
	global_load_lds_dwordx4 v[148:149], off
	v_lshl_add_u64 v[148:149], s[62:63], 0, v[130:131]
	s_mov_b32 m0, s64
	s_nop 0
	global_load_lds_dwordx4 v[148:149], off
	v_lshl_add_u64 v[148:149], s[62:63], 0, v[134:135]
	s_add_i32 m0, s64, 0x2000
	s_nop 0
	global_load_lds_dwordx4 v[148:149], off
	v_lshl_add_u64 v[148:149], v[220:221], 0, s[16:17]
	s_mov_b32 m0, s70
	s_nop 0
	global_load_lds_dwordx4 v[148:149], off
	v_lshl_add_u64 v[148:149], v[222:223], 0, s[16:17]
	s_mov_b32 m0, s71
	s_nop 0
	global_load_lds_dwordx4 v[148:149], off
	s_waitcnt vmcnt(8)
	s_waitcnt lgkmcnt(0)
	s_barrier
	s_setprio 1
	s_waitcnt lgkmcnt(0)
	v_mfma_f32_16x16x32_bf16 v[60:63], v[144:147], v[186:189], v[60:63]
	v_mfma_f32_16x16x32_bf16 v[56:59], v[162:165], v[186:189], v[56:59]
	v_mfma_f32_16x16x32_bf16 v[44:47], v[144:147], v[194:197], v[44:47]
	v_mfma_f32_16x16x32_bf16 v[40:43], v[162:165], v[194:197], v[40:43]
	v_mfma_f32_16x16x32_bf16 v[28:31], v[144:147], v[202:205], v[28:31]
	v_mfma_f32_16x16x32_bf16 v[24:27], v[162:165], v[202:205], v[24:27]
	v_mfma_f32_16x16x32_bf16 v[12:15], v[144:147], v[210:213], v[12:15]
	v_mfma_f32_16x16x32_bf16 v[8:11], v[162:165], v[210:213], v[8:11]
	v_mfma_f32_16x16x32_bf16 v[60:63], v[158:161], v[190:193], v[60:63]
	v_mfma_f32_16x16x32_bf16 v[56:59], v[166:169], v[190:193], v[56:59]
	v_mfma_f32_16x16x32_bf16 v[44:47], v[158:161], v[198:201], v[44:47]
	v_mfma_f32_16x16x32_bf16 v[40:43], v[166:169], v[198:201], v[40:43]
	v_mfma_f32_16x16x32_bf16 v[28:31], v[158:161], v[206:209], v[28:31]
	v_mfma_f32_16x16x32_bf16 v[24:27], v[166:169], v[206:209], v[24:27]
	v_mfma_f32_16x16x32_bf16 v[12:15], v[158:161], v[214:217], v[12:15]
	v_mfma_f32_16x16x32_bf16 v[8:11], v[166:169], v[214:217], v[8:11]
	s_setprio 0
	s_setprio 1
	v_mfma_f32_16x16x32_bf16 v[52:55], v[170:173], v[186:189], v[52:55]
	v_mfma_f32_16x16x32_bf16 v[48:51], v[178:181], v[186:189], v[48:51]
	v_mfma_f32_16x16x32_bf16 v[36:39], v[170:173], v[194:197], v[36:39]
	v_mfma_f32_16x16x32_bf16 v[32:35], v[178:181], v[194:197], v[32:35]
	v_mfma_f32_16x16x32_bf16 v[20:23], v[170:173], v[202:205], v[20:23]
	v_mfma_f32_16x16x32_bf16 v[16:19], v[178:181], v[202:205], v[16:19]
	v_mfma_f32_16x16x32_bf16 v[4:7], v[170:173], v[210:213], v[4:7]
	v_mfma_f32_16x16x32_bf16 v[0:3], v[178:181], v[210:213], v[0:3]
	v_mfma_f32_16x16x32_bf16 v[52:55], v[174:177], v[190:193], v[52:55]
	v_mfma_f32_16x16x32_bf16 v[48:51], v[182:185], v[190:193], v[48:51]
	v_mfma_f32_16x16x32_bf16 v[36:39], v[174:177], v[198:201], v[36:39]
	v_mfma_f32_16x16x32_bf16 v[32:35], v[182:185], v[198:201], v[32:35]
	v_mfma_f32_16x16x32_bf16 v[20:23], v[174:177], v[206:209], v[20:23]
	v_mfma_f32_16x16x32_bf16 v[16:19], v[182:185], v[206:209], v[16:19]
	v_mfma_f32_16x16x32_bf16 v[4:7], v[174:177], v[214:217], v[4:7]
	v_mfma_f32_16x16x32_bf16 v[0:3], v[182:185], v[214:217], v[0:3]
	s_setprio 0
	s_barrier
	s_add_i32 s83, s83, 2
	s_add_u32 s60, s60, 0x100
	s_addc_u32 s61, s61, 0
	s_add_u32 s81, s81, 0x100
	s_addc_u32 s82, s82, 0
	s_cmp_gt_u32 s83, 29
	s_cbranch_scc0 .LBB0_672
	s_and_b64 vcc, exec, s[38:39]
	s_cbranch_vccz .LBB0_675
	s_barrier
